# K-loop head aligned to 64 bytes
# speedup vs baseline: 1.0035x; 1.0035x over previous
.LBB0_245:
	s_and_b32 s9, s76, 7
	s_add_u32 s5, s58, s50
	s_addc_u32 s6, s59, s51
	s_lshl_b32 s8, s8, 3
	s_or_b32 s8, s8, s9
	s_lshl_b32 s7, s7, 3
	s_sub_i32 s7, s8, s7
	s_lshl_b32 s8, s7, 8
	s_ashr_i32 s9, s8, 31
	s_lshl_b64 s[8:9], s[8:9], 11
	s_add_u32 s8, s56, s8
	v_mov_b32_e32 v2, 0
	s_addc_u32 s9, s57, s9
	s_mov_b32 s7, 0
	s_mov_b64 s[50:51], 0
	s_mov_b32 s100, 0
	v_mov_b32_e32 v3, v2
	v_mov_b32_e32 v4, v2
	v_mov_b32_e32 v5, v2
	v_mov_b32_e32 v6, v2
	v_mov_b32_e32 v7, v2
	v_mov_b32_e32 v8, v2
	v_mov_b32_e32 v9, v2
	v_mov_b32_e32 v10, v2
	v_mov_b32_e32 v11, v2
	v_mov_b32_e32 v12, v2
	v_mov_b32_e32 v13, v2
	v_mov_b32_e32 v14, v2
	v_mov_b32_e32 v15, v2
	v_mov_b32_e32 v16, v2
	v_mov_b32_e32 v17, v2
	v_mov_b32_e32 v22, v2
	v_mov_b32_e32 v23, v2
	v_mov_b32_e32 v24, v2
	v_mov_b32_e32 v25, v2
	v_mov_b32_e32 v30, v2
	v_mov_b32_e32 v31, v2
	v_mov_b32_e32 v32, v2
	v_mov_b32_e32 v33, v2
	v_mov_b32_e32 v38, v2
	v_mov_b32_e32 v39, v2
	v_mov_b32_e32 v40, v2
	v_mov_b32_e32 v41, v2
	v_mov_b32_e32 v46, v2
	v_mov_b32_e32 v47, v2
	v_mov_b32_e32 v48, v2
	v_mov_b32_e32 v49, v2
	v_mov_b32_e32 v18, v2
	v_mov_b32_e32 v19, v2
	v_mov_b32_e32 v20, v2
	v_mov_b32_e32 v21, v2
	v_mov_b32_e32 v26, v2
	v_mov_b32_e32 v27, v2
	v_mov_b32_e32 v28, v2
	v_mov_b32_e32 v29, v2
	v_mov_b32_e32 v34, v2
	v_mov_b32_e32 v35, v2
	v_mov_b32_e32 v36, v2
	v_mov_b32_e32 v37, v2
	v_mov_b32_e32 v42, v2
	v_mov_b32_e32 v43, v2
	v_mov_b32_e32 v44, v2
	v_mov_b32_e32 v45, v2
	v_mov_b32_e32 v54, v2
	v_mov_b32_e32 v55, v2
	v_mov_b32_e32 v56, v2
	v_mov_b32_e32 v57, v2
	v_mov_b32_e32 v62, v2
	v_mov_b32_e32 v63, v2
	v_mov_b32_e32 v64, v2
	v_mov_b32_e32 v65, v2
	v_mov_b32_e32 v70, v2
	v_mov_b32_e32 v71, v2
	v_mov_b32_e32 v72, v2
	v_mov_b32_e32 v73, v2
	v_mov_b32_e32 v78, v2
	v_mov_b32_e32 v79, v2
	v_mov_b32_e32 v80, v2
	v_mov_b32_e32 v81, v2
	v_mov_b32_e32 v50, v2
	v_mov_b32_e32 v51, v2
	v_mov_b32_e32 v52, v2
	v_mov_b32_e32 v53, v2
	v_mov_b32_e32 v58, v2
	v_mov_b32_e32 v59, v2
	v_mov_b32_e32 v60, v2
	v_mov_b32_e32 v61, v2
	v_mov_b32_e32 v66, v2
	v_mov_b32_e32 v67, v2
	v_mov_b32_e32 v68, v2
	v_mov_b32_e32 v69, v2
	v_mov_b32_e32 v74, v2
	v_mov_b32_e32 v75, v2
	v_mov_b32_e32 v76, v2
	v_mov_b32_e32 v77, v2
	v_mov_b32_e32 v86, v2
	v_mov_b32_e32 v87, v2
	v_mov_b32_e32 v88, v2
	v_mov_b32_e32 v89, v2
	v_mov_b32_e32 v94, v2
	v_mov_b32_e32 v95, v2
	v_mov_b32_e32 v96, v2
	v_mov_b32_e32 v97, v2
	v_mov_b32_e32 v102, v2
	v_mov_b32_e32 v103, v2
	v_mov_b32_e32 v104, v2
	v_mov_b32_e32 v105, v2
	v_mov_b32_e32 v110, v2
	v_mov_b32_e32 v111, v2
	v_mov_b32_e32 v112, v2
	v_mov_b32_e32 v113, v2
	v_mov_b32_e32 v82, v2
	v_mov_b32_e32 v83, v2
	v_mov_b32_e32 v84, v2
	v_mov_b32_e32 v85, v2
	v_mov_b32_e32 v90, v2
	v_mov_b32_e32 v91, v2
	v_mov_b32_e32 v92, v2
	v_mov_b32_e32 v93, v2
	v_mov_b32_e32 v98, v2
	v_mov_b32_e32 v99, v2
	v_mov_b32_e32 v100, v2
	v_mov_b32_e32 v101, v2
	v_mov_b32_e32 v106, v2
	v_mov_b32_e32 v107, v2
	v_mov_b32_e32 v108, v2
	v_mov_b32_e32 v109, v2
	v_mov_b32_e32 v114, v2
	v_mov_b32_e32 v115, v2
	v_mov_b32_e32 v116, v2
	v_mov_b32_e32 v117, v2
	v_mov_b32_e32 v118, v2
	v_mov_b32_e32 v119, v2
	v_mov_b32_e32 v120, v2
	v_mov_b32_e32 v121, v2
	v_mov_b32_e32 v122, v2
	v_mov_b32_e32 v123, v2
	v_mov_b32_e32 v124, v2
	v_mov_b32_e32 v125, v2
	v_mov_b32_e32 v126, v2
	v_mov_b32_e32 v127, v2
	v_mov_b32_e32 v128, v2
	v_mov_b32_e32 v129, v2
	.p2align 6
